# P0 reorder v2 + pool/conv units per CU rebalanced (1,5) against the context-attention units
# baseline (speedup 1.0000x reference)
.LBB0_242:
	s_or_b64 exec, exec, s[4:5]
	s_cmpk_lg_i32 s16, 0x100
	s_cselect_b64 s[0:1], -1, 0
	s_cmpk_eq_i32 s16, 0x100
	v_writelane_b32 v254, s0, 0
	s_movk_i32 s4, 0x800
	s_mul_i32 s70, s17, s16
	v_writelane_b32 v254, s1, 1
	s_cselect_b64 s[0:1], -1, 0
	v_writelane_b32 v254, s0, 2
	s_mul_i32 s70, s70, s3
	s_mov_b32 s47, 0
	v_writelane_b32 v254, s1, 3
	s_and_b64 s[0:1], s[0:1], exec
	s_cselect_b32 s22, s4, 0x840
	s_cselect_b32 s24, s16, 0x180
	s_cmp_lt_i32 s2, s22
	s_cselect_b64 s[0:1], -1, 0
	v_writelane_b32 v254, s0, 4
	s_ashr_i32 s17, s2, 31
	s_and_b32 s21, s2, 15
	v_writelane_b32 v254, s1, 5
	s_lshr_b32 s0, s17, 29
	s_add_i32 s0, s2, s0
	s_ashr_i32 s7, s0, 3
	s_and_b32 s0, s0, -8
	s_or_b32 s4, s21, 0xb0
	s_ashr_i32 s6, s2, 4
	s_sub_i32 s12, s2, s0
	s_add_i32 s0, s6, 14
	s_lshl_b32 s1, s4, 18
	v_writelane_b32 v254, s1, 6
	s_ashr_i32 s1, s0, 31
	s_lshl_b64 s[8:9], s[0:1], 19
	s_lshr_b32 s86, s22, 3
	v_writelane_b32 v254, s8, 7
	s_lshl_b32 s1, s4, 7
	s_lshl_b32 s4, s0, 8
	s_or_b32 s87, s86, 1
	s_ashr_i32 s39, s16, 31
	v_writelane_b32 v254, s9, 8
	s_ashr_i32 s5, s4, 31
	s_lshl_b32 s0, s0, 7
	v_writelane_b32 v254, s1, 9
	s_cmpk_lt_i32 s2, 0x240
	v_writelane_b32 v254, s0, 10
	s_cselect_b64 s[0:1], -1, 0
	v_writelane_b32 v254, s0, 11
	s_cmpk_lt_i32 s2, 0x180
	s_mov_b32 s19, s47
	v_writelane_b32 v254, s1, 12
	s_cselect_b64 s[0:1], -1, 0
	v_writelane_b32 v254, s0, 13
	s_cmpk_lt_i32 s2, 0x300
	s_mov_b32 s23, s47
	v_writelane_b32 v254, s1, 14
	s_cselect_b64 s[0:1], -1, 0
	v_writelane_b32 v254, s0, 15
	s_mov_b32 s8, s2
	s_mov_b32 s25, s47
	v_writelane_b32 v254, s1, 16
	s_mul_i32 s0, s2, 5
	s_add_i32 s9, s0, 0xfffffe00
	s_cmpk_lt_i32 s2, 0x80
	s_cselect_b64 s[0:1], -1, 0
	v_writelane_b32 v254, s0, 17
	s_movk_i32 s71, 0x1600
	s_mov_b64 s[62:63], 0x5000000
	v_writelane_b32 v254, s1, 18
	s_and_b64 s[0:1], s[0:1], exec
	s_cselect_b32 s67, s8, s9
	s_cselect_b32 s81, 1, 5
	s_lshl_b32 s1, s67, 5
	s_and_b32 s8, s1, 0xffffff00
	s_and_b32 s10, s1, 0x7ffff000
	s_add_i32 s9, s8, 0x100
	s_add_i32 s11, s10, 0x1000
	s_cmpk_lt_i32 s67, 0x100
	s_cselect_b32 s0, s9, s11
	v_writelane_b32 v254, s0, 19
	s_cselect_b32 s0, s8, s10
	v_writelane_b32 v254, s0, 20
	s_add_i32 s0, s1, -15
	v_writelane_b32 v254, s0, 21
	s_add_i32 s0, s1, -8
	s_cmp_lt_i32 s2, s24
	v_writelane_b32 v254, s0, 22
	s_cselect_b64 s[0:1], -1, 0
	v_writelane_b32 v254, s0, 23
	s_mov_b32 s11, s47
	s_waitcnt lgkmcnt(0)
	v_mov_b32_e32 v0, 0
	v_writelane_b32 v254, s1, 24
	s_lshr_b32 s0, s24, 3
	s_cmpk_lt_i32 s2, 0x100
	s_cselect_b64 s[8:9], -1, 0
	v_writelane_b32 v254, s8, 25
	s_and_b32 s1, s33, 56
	s_mov_b64 s[76:77], 0x80
	v_writelane_b32 v254, s9, 26
	s_bfe_u32 s8, s2, 0x30003
	s_or_b32 s1, s8, s1
	s_or_b32 s8, s1, 0x80
	s_ashr_i32 s9, s2, 6
	v_writelane_b32 v254, s8, 27
	v_writelane_b32 v254, s9, 28
	s_lshl_b32 s9, s9, 8
	s_lshl_b32 s8, s8, 7
	v_writelane_b32 v254, s9, 29
	v_writelane_b32 v254, s8, 30
	s_addk_i32 s8, 0xe000
	s_lshr_b32 s8, s8, 12
	s_add_i32 s8, s8, 1
	s_lshl_b32 s10, s8, 10
	s_cmp_lt_i32 s12, 0
	s_cselect_b32 s3, s87, s86
	s_mul_i32 s46, s8, 0x2400
	s_mul_i32 s3, s3, s12
	s_movk_i32 s8, 0x49
	s_cselect_b32 s13, s8, 0x48
	s_add_i32 s3, s3, s7
	s_mul_hi_i32 s8, s3, 0x2e8ba2e9
	s_lshr_b32 s9, s8, 31
	s_ashr_i32 s8, s8, 5
	s_add_i32 s8, s8, s9
	s_mul_i32 s9, s8, 0xb0
	v_writelane_b32 v254, s10, 31
	s_sub_i32 s3, s3, s9
	v_mov_b32_e32 v229, 0x358637bd
	v_writelane_b32 v254, s11, 32
	s_lshl_b32 s10, s8, 3
	s_bfe_u32 s8, s3, 0x3001c
	s_add_i32 s9, s3, s8
	s_sext_i32_i16 s11, s9
	s_and_b32 s9, s9, 0xfff8
	s_sub_i32 s3, s3, s9
	s_sext_i32_i16 s3, s3
	s_add_i32 s14, s10, s3
	s_ashr_i32 s15, s14, 31
	s_lshr_b32 s8, s11, 3
	s_ashr_i32 s20, s11, 3
	s_lshl_b64 s[10:11], s[14:15], 19
	v_writelane_b32 v254, s10, 33
	s_bfe_i64 s[8:9], s[8:9], 0x100000
	s_lshl_b64 s[8:9], s[8:9], 19
	v_writelane_b32 v254, s11, 34
	s_lshl_b32 s10, s14, 8
	s_add_i32 s3, s10, 0xffffe000
	s_lshr_b32 s3, s3, 12
	s_mulk_i32 s3, 0x1600
	s_ashr_i32 s11, s10, 31
	s_addk_i32 s3, 0x1600
	v_writelane_b32 v254, s8, 35
	s_cmp_gt_i32 s14, 31
	s_cselect_b32 s18, s3, 0
	v_writelane_b32 v254, s9, 36
	s_mov_b32 s8, s14
	s_mul_i32 s3, s12, s13
	v_writelane_b32 v254, s8, 37
	s_add_i32 s3, s3, s7
	s_lshl_b32 s26, s20, 8
	v_writelane_b32 v254, s9, 38
	s_mul_hi_i32 s8, s3, 0x2aaaaaab
	s_lshr_b32 s9, s8, 31
	s_ashr_i32 s8, s8, 3
	s_add_i32 s8, s8, s9
	s_lshl_b32 s9, s8, 3
	s_mul_i32 s8, s8, 48
	s_sub_i32 s3, s3, s8
	s_bfe_i32 s8, s3, 0x80000
	s_bfe_u32 s8, s8, 0x3000c
	s_add_i32 s13, s3, s8
	s_bfe_i32 s8, s13, 0x80000
	s_and_b32 s13, s13, 0xf8
	s_sub_i32 s3, s3, s13
	s_sext_i32_i8 s3, s3
	s_add_i32 s28, s9, s3
	s_lshr_b32 s3, s12, 31
	s_or_b32 s3, s0, s3
	s_mul_i32 s3, s3, s12
	s_add_i32 s3, s3, s7
	s_ashr_i32 s7, s3, 31
	s_lshr_b32 s7, s7, 27
	s_add_i32 s7, s3, s7
	s_ashr_i32 s9, s7, 5
	s_and_b32 s7, s7, 0xffe0
	s_sub_i32 s3, s3, s7
	s_bfe_i32 s7, s3, 0x80000
	s_bfe_u32 s7, s7, 0x3000c
	s_add_i32 s7, s3, s7
	s_bfe_i32 s12, s7, 0x80000
	s_and_b32 s7, s7, 0xf8
	s_sub_i32 s3, s3, s7
	v_writelane_b32 v254, s20, 39
	s_lshl_b32 s9, s9, 3
	s_sext_i32_i8 s3, s3
	v_writelane_b32 v254, s0, 40
	s_sext_i32_i16 s12, s12
	s_add_i32 s0, s9, s3
	s_sext_i32_i16 s14, s8
	v_writelane_b32 v254, s0, 41
	s_ashr_i32 s0, s12, 3
	s_ashr_i32 s29, s28, 31
	s_lshr_b32 s8, s14, 3
	s_lshr_b32 s20, s12, 3
	v_writelane_b32 v254, s0, 42
	s_lshl_b64 s[12:13], s[28:29], 19
	v_writelane_b32 v254, s12, 43
	s_bfe_i64 s[8:9], s[8:9], 0x100000
	s_lshl_b64 s[8:9], s[8:9], 19
	v_writelane_b32 v254, s13, 44
	v_writelane_b32 v254, s8, 45
	s_mov_b32 s0, s28
	s_ashr_i32 s27, s26, 31
	v_writelane_b32 v254, s9, 46
	s_lshl_b32 s8, s28, 8
	s_add_i32 s3, s8, 0xffffe000
	s_lshr_b32 s3, s3, 12
	s_mulk_i32 s3, 0x600
	s_ashr_i32 s14, s14, 3
	s_ashr_i32 s9, s8, 31
	s_addk_i32 s3, 0x600
	v_writelane_b32 v254, s0, 47
	s_cmp_gt_i32 s28, 31
	s_cselect_b32 s12, s3, 0
	v_writelane_b32 v254, s1, 48
	v_writelane_b32 v254, s14, 49
	s_bfe_i64 s[28:29], s[20:21], 0x100000
	v_writelane_b32 v254, s28, 50
	s_lshl_b32 s14, s14, 8
	s_lshl_b32 s0, s21, 18
	v_writelane_b32 v254, s29, 51
	s_ashr_i32 s7, s6, 31
	s_ashr_i32 s15, s14, 31
	v_writelane_b32 v254, s0, 52
	s_or_b32 s0, s0, 0x7c00080
	s_lshl_b64 s[6:7], s[6:7], 19
	v_writelane_b32 v254, s0, 53
	s_add_u32 s0, s6, 0xb00100
	v_writelane_b32 v254, s0, 54
	s_addc_u32 s0, s7, 0
	s_lshl_b32 s1, s1, 8
	v_writelane_b32 v254, s0, 55
	s_or_b32 s0, s1, 0x8000
	v_writelane_b32 v254, s0, 56
	s_lshl_b64 s[0:1], s[10:11], 2
	v_writelane_b32 v254, s0, 57
	s_mov_b32 s13, s47
	s_add_i32 s88, 0, 0x200c8
	v_writelane_b32 v254, s1, 58
	s_lshl_b64 s[0:1], s[18:19], 2
	v_writelane_b32 v254, s0, 59
	s_add_i32 s89, 0, 0x200cc
	s_mov_b32 s92, 0x800000
	v_writelane_b32 v254, s1, 60
	s_lshl_b64 s[0:1], s[26:27], 2
	v_writelane_b32 v254, s0, 61
	s_mov_b64 s[78:79], 0x8000000
	s_add_i32 s93, 0, 0x200c0
	v_writelane_b32 v254, s1, 62
	s_lshl_b64 s[0:1], s[4:5], 2
	v_writelane_b32 v254, s0, 63
	s_add_i32 s94, 0, 0x200c4
	s_add_i32 s95, 0, 0x200a8
	v_writelane_b32 v255, s1, 0
	s_lshl_b64 s[0:1], s[8:9], 2
	v_writelane_b32 v255, s0, 1
	s_add_i32 s96, 0, 0x200ac
	s_add_i32 s97, 0, 0x200b0
	v_writelane_b32 v255, s1, 2
	s_lshl_b64 s[0:1], s[12:13], 2
	v_writelane_b32 v255, s0, 3
	s_add_i32 s28, 0, 0x200b4
	v_mov_b32_e32 v252, 0x1000
	v_writelane_b32 v255, s1, 4
	s_lshl_b64 s[0:1], s[14:15], 2
	v_writelane_b32 v255, s0, 5
	v_mov_b32_e32 v253, 0x2000
	v_mov_b32_e32 v235, 1
	v_writelane_b32 v255, s1, 6
	s_add_i32 s0, 0, 0x20100
	v_writelane_b32 v255, s0, 7
	s_add_i32 s0, 0, 0x20104
	v_writelane_b32 v255, s0, 8
	s_add_i32 s0, 0, 0x10400
	v_writelane_b32 v255, s0, 9
	s_add_i32 s0, 0, 0x10800
	v_writelane_b32 v255, s0, 10
	s_add_i32 s0, 0, 0x10c00
	v_writelane_b32 v255, s0, 11
	s_add_i32 s0, 0, 0x11000
	v_writelane_b32 v255, s0, 12
	s_add_i32 s0, 0, 0x11400
	v_writelane_b32 v255, s0, 13
	s_add_i32 s0, 0, 0x11800
	v_writelane_b32 v255, s0, 14
	s_add_i32 s0, 0, 0x20088
	v_writelane_b32 v255, s0, 15
	s_add_i32 s0, 0, 0x2008c
	v_writelane_b32 v255, s0, 16
	s_add_i32 s0, 0, 0x20090
	v_writelane_b32 v255, s0, 17
	s_add_i32 s0, 0, 0x20094
	v_writelane_b32 v255, s0, 18
	s_add_i32 s0, 0, 0x20098
	v_writelane_b32 v255, s0, 19
	s_add_i32 s0, 0, 0x2009c
	v_writelane_b32 v255, s0, 20
	s_lshl_b64 s[0:1], s[46:47], 2
	v_writelane_b32 v255, s0, 21
	s_add_i32 s29, 0, 0x200b8
	s_add_i32 s90, 0, 0x200bc
	v_writelane_b32 v255, s1, 22
	v_writelane_b32 v255, s72, 23
	s_movk_i32 s91, 0xfefe
	s_mov_b32 s33, 0x41000000
	v_writelane_b32 v255, s73, 24
	v_writelane_b32 v255, s86, 25
	v_writelane_b32 v255, s87, 26
	s_mov_b32 s80, 0x3b800000
	s_mov_b32 s64, 0x358637bd
	s_mov_b64 s[48:49], 0x3a2000
	s_mov_b64 s[54:55], 0x10480000
	s_mov_b64 s[18:19], 0x104c0000
	v_mov_b32_e32 v234, 0xf149f2ca
	v_mov_b32_e32 v236, 63
	s_mov_b32 s74, 0
	v_writelane_b32 v255, s67, 27
	s_barrier
	s_branch .LBB0_246
